# attention unit prologue: redundant first vmcnt(0) dropped (the vmcnt(0) after the first K/V pair covers the Q loads); on top of v91
# baseline (speedup 1.0000x reference)
; #define LAS __attribute__((address_space(3)))
; #define GAS __attribute__((address_space(1)))
; #define AT_WAIT0(src) asm volatile("s_waitcnt vmcnt(0)" : "+v"(src[0]), "+v"(src[1]), "+v"(src[2]), "+v"(src[3]) :: "memory")
; #define AT_STORE(src, stage) do { _Pragma("unroll") for (int q_ = 0; q_ < 4; ++q_) *(LAS u32x4*)(wr0 + (stage) * AT_STAGE + q_ * AT_TILE) = src[q_]; } while (0)
; __device__ __forceinline__ void attn_unit(LAS unsigned char* lds, const bf16* PROJ, bf16* YMIX, float* ssq, const float* relb, const float* gqn, const float* gkn,
;                                           int b, int h, int c0, int wave, int lane_in, int tid_in) {
;     ...
;     const size_t tok0 = (size_t)b * SEQ + (size_t)(c0 + par) * 64 + 16 * r4;
;     bf16x8 qf[4][2];
; #pragma unroll
;     for (int nq = 0; nq < 4; ++nq)
; #pragma unroll
;         for (int kk = 0; kk < 2; ++kk) qf[nq][kk] = __builtin_nontemporal_load((const GAS bf16x8*)(PROJ + (tok0 + 128 * nq + fr) * NPROJ + h * 64 + 32 * kk + 8 * fq));
;     f32x4 O[4][4], L[4];
;     const bf16x8 ones8 = {(short)0x3f80, (short)0x3f80, (short)0x3f80, (short)0x3f80, (short)0x3f80, (short)0x3f80, (short)0x3f80, (short)0x3f80};
; #pragma unroll
;     for (int md = 0; md < 4; ++md)
; #pragma unroll
;         for (int nq = 0; nq < 4; ++nq) O[md][nq] = (f32x4){0.f, 0.f, 0.f, 0.f};
; #pragma unroll
;     for (int nq = 0; nq < 4; ++nq) L[nq] = (f32x4){0.f, 0.f, 0.f, 0.f};
;     const int j0 = (c0 == 0) ? 8 : 0;
;     const int skey = tid >> 3, sd = (tid & 7) * 8;
;     const bf16* Kg = PROJ + ((size_t)b * SEQ + (size_t)((c0 - 8 + j0) * 64 + skey)) * NPROJ + 512 + h * 64 + sd;
;     const LAS unsigned char* const rd0 = lds;
;     LAS unsigned char* const wr0 = lds + skey * KP + sd * 2;
;     const bf16* Kg2 = Kg + (size_t)64 * NPROJ;
;     u32x4 pa[4], pb[4];
;     ...
;     asm volatile("s_waitcnt vmcnt(0)" ::: "memory");
;     AT_GLOAD(pa); AT_WAIT0(pa); AT_STORE(pa, 0);
;     AT_GLOAD(pb);
;     AT_GLOAD(pa);
.LBB0_327:
	s_mov_b32 s4, s27
	s_mov_b32 s4, s27
	s_mov_b32 s4, s27
	v_mov_b32_e32 v0, 0
	s_mov_b32 s4, s3
	v_mbcnt_lo_u32_b32 v0, -1, v0
	v_mbcnt_hi_u32_b32 v231, -1, v0
	v_mov_b32_e32 v0, 0
	s_or_b32 s13, s82, s96
	v_mbcnt_lo_u32_b32 v0, -1, v0
	v_mbcnt_hi_u32_b32 v0, -1, v0
	v_lshl_add_u32 v0, s4, 6, v0
	v_mov_b32_e32 v5, v231
	s_mov_b32 s15, s3
	s_lshl_b32 s14, s13, 3
	s_ashr_i32 s85, s15, 2
	s_add_i32 s4, s85, s14
	s_ashr_i32 s5, s4, 31
	s_lshl_b64 s[4:5], s[4:5], 6
	s_add_u32 s4, s4, s22
	v_ashrrev_i32_e32 v25, 4, v5
	s_addc_u32 s65, s5, s23
	s_lshl_b32 s5, s15, 4
	s_and_b32 s15, s5, 48
	v_lshlrev_b32_e32 v2, 3, v25
	v_and_b32_e32 v24, 15, v5
	s_or_b32 s64, s4, s15
	v_ashrrev_i32_e32 v3, 31, v2
	v_or_b32_e32 v8, s64, v24
	v_lshl_add_u64 v[2:3], v[2:3], 1, s[8:9]
	v_mad_u64_u32 v[2:3], s[4:5], v8, s44, v[2:3]
	s_mov_b32 s4, 0xc0000
	v_mad_i32_i24 v3, s65, v224, v3
	v_add_co_u32_e32 v8, vcc, s4, v2
	s_mov_b32 s4, 0x180000
	s_nop 0
	v_addc_co_u32_e32 v9, vcc, 0, v3, vcc
	global_load_dwordx4 v[64:67], v[2:3], off nt
	global_load_dwordx4 v[68:71], v[2:3], off offset:64 nt
	global_load_dwordx4 v[76:79], v[8:9], off nt
	global_load_dwordx4 v[80:83], v[8:9], off offset:64 nt
	v_add_co_u32_e32 v8, vcc, s4, v2
	s_mov_b32 s4, 0x240000
	s_nop 0
	v_addc_co_u32_e32 v9, vcc, 0, v3, vcc
	v_add_co_u32_e32 v2, vcc, s4, v2
	global_load_dwordx4 v[84:87], v[8:9], off nt
	global_load_dwordx4 v[88:91], v[8:9], off offset:64 nt
	v_addc_co_u32_e32 v3, vcc, 0, v3, vcc
	global_load_dwordx4 v[92:95], v[2:3], off nt
	global_load_dwordx4 v[96:99], v[2:3], off offset:64 nt
	s_cmp_eq_u32 s13, 0
	s_cselect_b32 s13, 8, 0
	s_add_i32 s14, s14, s13
	s_lshl_b32 s4, s14, 6
	v_ashrrev_i32_e32 v8, 3, v0
	s_addk_i32 s4, 0xfe00
	v_add_u32_e32 v2, s4, v8
	v_ashrrev_i32_e32 v3, 31, v2
	v_mov_b64_e32 v[6:7], s[8:9]
	v_lshl_add_u64 v[2:3], s[22:23], 0, v[2:3]
	v_mad_u64_u32 v[6:7], s[4:5], v2, s44, v[6:7]
	v_lshlrev_b32_e32 v0, 4, v0
	v_mad_i32_i24 v7, v3, s44, v7
	v_and_b32_e32 v0, 0x70, v0
	v_lshl_add_u64 v[2:3], v[6:7], 0, v[0:1]
	v_mul_lo_u32 v6, v8, s29
	s_mov_b64 s[4:5], 0x400
	v_add_u32_e32 v6, 0, v6
	s_nop 0
	v_lshl_add_u64 v[14:15], v[2:3], 0, s[4:5]
	v_add_u32_e32 v232, v6, v0
	global_load_dwordx4 v[6:9], v[14:15], off
	s_mov_b64 s[4:5], 0x60400
	global_load_dwordx4 v[10:13], v[14:15], off offset:1024
	v_lshl_add_u64 v[22:23], v[2:3], 0, s[4:5]
	global_load_dwordx4 v[14:17], v[22:23], off
	global_load_dwordx4 v[18:21], v[22:23], off offset:1024
	s_mov_b64 s[4:5], 0xc0400
	s_waitcnt vmcnt(0)
	ds_write_b128 v232, v[6:9]
	ds_write_b128 v232, v[10:13] offset:9216
	ds_write_b128 v232, v[14:17] offset:18432
	ds_write_b128 v232, v[18:21] offset:27648
	v_lshl_add_u64 v[22:23], v[2:3], 0, s[4:5]
	global_load_dwordx4 v[112:115], v[22:23], off
	s_mov_b64 s[4:5], 0x120400
	global_load_dwordx4 v[116:119], v[22:23], off offset:1024
	v_lshl_add_u64 v[6:7], v[2:3], 0, s[4:5]
	global_load_dwordx4 v[124:127], v[6:7], off
	s_mov_b64 s[4:5], 0x180400
	global_load_dwordx4 v[128:131], v[6:7], off offset:1024
	v_lshl_add_u64 v[6:7], v[2:3], 0, s[4:5]
	s_mov_b64 s[4:5], 0x1e0400
	v_lshl_add_u64 v[8:9], v[2:3], 0, s[4:5]
	s_mov_b64 s[4:5], 0x2a0400
	v_lshl_add_u64 v[208:209], v[2:3], 0, s[4:5]
	s_mov_b64 s[4:5], 0x240400
	v_lshl_add_u64 v[210:211], v[2:3], 0, s[4:5]
	v_lshlrev_b32_e32 v2, 2, v25
	v_bfe_u32 v3, v5, 2, 2
	global_load_dwordx4 v[132:135], v[6:7], off
	v_or_b32_e32 v3, v2, v3
	global_load_dwordx4 v[140:143], v[6:7], off offset:1024
	v_mul_lo_u32 v3, v3, s29
	v_or_b32_e32 v7, s15, v24
	global_load_dwordx4 v[144:147], v[8:9], off
	v_and_b32_e32 v0, -16, v5
	v_lshlrev_b32_e32 v5, 3, v5
	v_add_u32_e32 v6, 0x900, v3
	v_sub_u32_e32 v2, v2, v7
	global_load_dwordx4 v[148:151], v[8:9], off offset:1024
	v_and_b32_e32 v5, 24, v5
	v_add_u32_e32 v233, 0xfffffe80, v2
	v_add_u32_e32 v7, 0, v0
	v_mul_u32_u24_e32 v8, 0x90, v24
	v_add_u32_e32 v9, 0, v3
	v_add_u32_e32 v10, 0, v6
	v_add_u32_e32 v234, 0xfffffea0, v2
	v_add_u32_e32 v11, s12, v3
	v_mov_b32_e32 v2, v1
	v_mov_b32_e32 v3, v1
	v_add_u32_e32 v6, s12, v6
	v_mov_b32_e32 v0, v1
	v_add_u32_e32 v235, v11, v5
	v_add_u32_e32 v237, v7, v8
	v_add_u32_e32 v238, v9, v5
	v_add_u32_e32 v239, v10, v5
	v_mov_b64_e32 v[10:11], v[2:3]
	v_mov_b64_e32 v[30:31], v[2:3]
	v_mov_b64_e32 v[50:51], v[2:3]
	v_mov_b64_e32 v[102:103], v[2:3]
	v_mov_b64_e32 v[14:15], v[2:3]
	v_mov_b64_e32 v[34:35], v[2:3]
	v_mov_b64_e32 v[54:55], v[2:3]
	v_mov_b64_e32 v[106:107], v[2:3]
	v_mov_b64_e32 v[18:19], v[2:3]
	v_mov_b64_e32 v[38:39], v[2:3]
	v_mov_b64_e32 v[58:59], v[2:3]
	v_mov_b64_e32 v[110:111], v[2:3]
	v_mov_b64_e32 v[22:23], v[2:3]
	v_mov_b64_e32 v[42:43], v[2:3]
	v_mov_b64_e32 v[62:63], v[2:3]
	v_mov_b64_e32 v[122:123], v[2:3]
	v_mov_b64_e32 v[26:27], v[2:3]
	v_mov_b64_e32 v[46:47], v[2:3]
	v_mov_b64_e32 v[74:75], v[2:3]
	v_mov_b64_e32 v[138:139], v[2:3]
	s_lshr_b32 s18, s13, 1
	s_add_i32 s19, s85, 2
	s_add_i32 s30, s85, 4
	s_add_i32 s34, s85, 6
	v_add_u32_e32 v236, v6, v5
	v_mov_b64_e32 v[8:9], v[0:1]
	v_mov_b64_e32 v[28:29], v[0:1]
	v_mov_b64_e32 v[48:49], v[0:1]
	v_mov_b64_e32 v[100:101], v[0:1]
	v_mov_b64_e32 v[12:13], v[0:1]
	v_mov_b64_e32 v[32:33], v[0:1]
	v_mov_b64_e32 v[52:53], v[0:1]
	v_mov_b64_e32 v[104:105], v[0:1]
	v_mov_b64_e32 v[16:17], v[0:1]
	v_mov_b64_e32 v[36:37], v[0:1]
	v_mov_b64_e32 v[56:57], v[0:1]
	v_mov_b64_e32 v[108:109], v[0:1]
	v_mov_b64_e32 v[20:21], v[0:1]
	v_mov_b64_e32 v[40:41], v[0:1]
	v_mov_b64_e32 v[60:61], v[0:1]
	v_mov_b64_e32 v[120:121], v[0:1]
	v_mov_b64_e32 v[24:25], v[0:1]
	v_mov_b64_e32 v[44:45], v[0:1]
	v_mov_b64_e32 v[72:73], v[0:1]
	v_mov_b64_e32 v[136:137], v[0:1]
	s_branch .LBB0_331
